# march: conflict-free rotated M^T layout for the transposed reads
# baseline (speedup 1.0000x reference)
.Lm_fwd_1:
	s_lshl_b32 s15, s7, 23
	s_lshl_b32 s96, s6, 22
	s_add_u32 s15, s15, s96
	s_lshl_b32 s96, s11, 16
	s_add_u32 s15, s15, s96
	s_add_u32 s15, s15, 0x1b000000
	s_add_u32 s38, s36, s15
	s_addc_u32 s39, s37, 0
	s_lshl_b32 s15, s8, 1
	s_add_u32 s15, s15, s5
	s_lshl_b32 s15, s15, 20
	s_lshl_b32 s96, s6, 19
	s_add_u32 s15, s15, s96
	s_lshl_b32 s96, s11, 13
	s_add_u32 s15, s15, s96
	s_add_u32 s15, s15, 0x17000000
	s_add_u32 s40, s36, s15
	s_addc_u32 s41, s37, 0
	s_lshl_b32 s15, s6, 21
	s_add_u32 s15, s15, s9
	s_lshl_b32 s96, s11, 15
	s_add_u32 s15, s15, s96
	s_add_u32 s15, s15, 0x1f000000
	s_add_u32 s42, s36, s15
	s_addc_u32 s43, s37, 0
	s_lshl_b32 s15, s6, 25
	s_lshl_b32 s96, s8, 7
	s_add_u32 s15, s15, s96
	s_lshl_b32 s96, s5, 6
	s_add_u32 s15, s15, s96
	s_lshl_b32 s96, s11, 19
	s_add_u32 s15, s15, s96
	s_lshl_b32 s96, s51, 26
	s_add_u32 s15, s15, s96
	s_add_u32 s15, s15, 0xf000000
	s_add_u32 s44, s36, s15
	s_addc_u32 s45, s37, 0
	s_lshl_b32 s4, s3, 2
	s_lshr_b32 s5, 0x2101233, s4
	s_and_b32 s5, s5, 3
	s_lshr_b32 s6, 0x2001020, s4
	s_and_b32 s6, s6, 3
	s_lshr_b32 s7, 0x1111222, s4
	s_and_b32 s52, s7, 3
	s_sub_i32 s8, 3, s5
	s_cmp_eq_u32 s52, 2
	s_cselect_b32 s97, 2, 3
	s_sub_i32 s97, s97, s6
	s_cmp_eq_u32 s51, 0
	s_cselect_b32 s13, s5, s8
	s_cselect_b32 s14, s6, s97
	s_cmp_eq_u32 s14, s13
	s_cselect_b32 s53, 1, 0
	s_add_u32 s4, s14, 1
	s_cmp_eq_u32 s4, s13
	s_cselect_b32 s54, 1, 0
	s_waitcnt lgkmcnt(0)
	v_mov_b32_e32 v1, s10
	v_mul_f32_e32 v1, 0x3fb8aa3b, v1
	v_exp_f32_e32 v1, v1
	s_nop 0
	v_xor_b32_e32 v1, 0x80000000, v1
	s_nop 0
	v_readfirstlane_b32 s62, v1
	v_and_b32_e32 v116, 31, v175
	v_bfe_u32 v117, v175, 5, 1
	v_bfe_u32 v118, v175, 2, 2
	v_and_b32_e32 v119, 3, v175
	v_bfe_u32 v120, v175, 4, 1
	v_and_b32_e32 v121, 63, v175
	v_lshlrev_b32_e32 v122, 5, v120
	v_lshl_add_u32 v122, v119, 3, v122
	v_lshl_add_u32 v123, v117, 3, v118
	v_lshrrev_b32_e32 v124, 4, v175
	v_and_b32_e32 v125, 15, v175
	v_lshlrev_b32_e32 v125, 4, v125
	v_lshl_add_u32 v164, v124, 9, v125
	v_add_u32_e32 v165, 0x4000, v164
	v_add_u32_e32 v166, 0x8000, v164
	v_add_u32_e32 v167, 0xc000, v164
	v_mad_u32_u24 v169, v124, s59, v125
	v_lshlrev_b32_e32 v168, 4, v175
	v_lshrrev_b32_e32 v126, 2, v175
	v_lshlrev_b32_e32 v127, 4, v119
	v_mad_u32_u24 v127, v126, s60, v127
	v_add_u32_e32 v170, 0x19800, v127
	v_lshlrev_b32_e32 v127, 2, v126
	v_add_u32_e32 v171, 0x23000, v127
	v_mov_b32_e32 v172, 0x23400
	s_lshl_b32 s4, s3, 5
	v_add_u32_e32 v128, s4, v116
	v_lshlrev_b32_e32 v129, 4, v117
	v_mad_u32_u24 v173, v128, s59, v129
	v_mad_u32_u24 v130, v116, s59, v129
	v_add_u32_e32 v210, 0x1e800, v130
	v_lshlrev_b32_e32 v130, 2, v128
	v_add_u32_e32 v211, 0x23000, v130
	v_lshlrev_b32_e32 v130, 3, v117
	v_lshl_add_u32 v212, v128, 12, v130
	v_mad_u32_u24 v130, v123, s60, v122
	v_add_u32_e32 v208, 0x19800, v130
	v_add_u32_e32 v192, 0x1c000, v130
	v_mad_u32_u24 v131, v123, s59, v122
	v_lshrrev_b32_e32 v130, 3, v122
	v_lshl_add_u32 v130, v118, 3, v130
	v_lshl_add_u32 v130, v117, 2, v130
	s_lshl_b32 s4, s3, 3
	v_add_u32_e32 v130, s4, v130
	v_add_u32_e32 v127, 2, v130
	v_and_b32_e32 v130, 31, v130
	v_and_b32_e32 v127, 31, v127
	v_lshlrev_b32_e32 v126, 8, v123
	v_lshl_add_u32 v130, v130, 3, v126
	v_lshl_add_u32 v127, v127, 3, v126
	v_add_u32_e32 v209, 0x11000, v130
	v_add_u32_e32 v110, 0x11400, v127
	s_sub_i32 s4, s3, 4
	s_lshl_b32 s4, s4, 6
	v_add_u32_e32 v130, s4, v131
	v_add_u32_e32 v193, 0x8800, v130
	v_lshlrev_b32_e32 v130, 3, v117
	v_mad_u32_u24 v130, v116, s59, v130
	v_add_u32_e32 v130, s4, v130
	v_add_u32_e32 v194, 0x1e800, v130
	v_lshlrev_b32_e32 v195, 9, v121
	v_lshlrev_b32_e32 v130, 3, v121
	v_add_u32_e32 v196, 0x23000, v130
	v_subrev_u32_e32 v130, 1, v121
	v_max_i32_e32 v130, 0, v130
	v_lshlrev_b32_e32 v197, 2, v130
	v_cmp_le_u32_e64 s[16:17], 1, v121
	v_subrev_u32_e32 v130, 2, v121
	v_max_i32_e32 v130, 0, v130
	v_lshlrev_b32_e32 v198, 2, v130
	v_cmp_le_u32_e64 s[18:19], 2, v121
	v_subrev_u32_e32 v130, 4, v121
	v_max_i32_e32 v130, 0, v130
	v_lshlrev_b32_e32 v199, 2, v130
	v_cmp_le_u32_e64 s[20:21], 4, v121
	v_subrev_u32_e32 v130, 8, v121
	v_max_i32_e32 v130, 0, v130
	v_lshlrev_b32_e32 v200, 2, v130
	v_cmp_le_u32_e64 s[22:23], 8, v121
	v_subrev_u32_e32 v130, 16, v121
	v_max_i32_e32 v130, 0, v130
	v_lshlrev_b32_e32 v201, 2, v130
	v_cmp_le_u32_e64 s[24:25], 16, v121
	v_subrev_u32_e32 v130, 32, v121
	v_max_i32_e32 v130, 0, v130
	v_lshlrev_b32_e32 v202, 2, v130
	v_cmp_le_u32_e64 s[26:27], 32, v121
	v_mov_b32_e32 v225, 0xfc
	s_lshl_b32 s4, s13, 5
	v_add_u32_e32 v130, s4, v116
	v_mad_u32_u24 v216, v130, s59, v129
	s_lshl_b32 s5, s14, 5
	v_add_u32_e32 v131, s5, v116
	v_mad_u32_u24 v217, v131, s59, v129
	s_lshl_b32 s6, s13, 7
	s_add_u32 s6, s6, 0x23000
	v_add_u32_e32 v222, s6, v129
	v_lshlrev_b32_e32 v130, 2, v131
	v_add_u32_e32 v223, 0x23000, v130
	v_and_b32_e32 v130, 3, v116
	v_lshlrev_b32_e32 v130, 3, v130
	v_bfe_u32 v126, v116, 2, 2
	v_lshl_add_u32 v130, v126, 1, v130
	v_add_u32_e32 v130, v117, v130
	s_lshl_b32 s6, s13, 3
	v_add_u32_e32 v130, s6, v130
	v_lshlrev_b32_e32 v126, 8, v131
	v_add_u32_e32 v126, 0x11000, v126
	v_add_u32_e32 v127, 0, v130
	v_and_b32_e32 v127, 31, v127
	v_lshl_add_u32 v224, v127, 3, v126
	v_add_u32_e32 v127, 2, v130
	v_and_b32_e32 v127, 31, v127
	v_lshl_add_u32 v3, v127, 3, v126
	v_add_u32_e32 v127, 4, v130
	v_and_b32_e32 v127, 31, v127
	v_lshl_add_u32 v108, v127, 3, v126
	v_add_u32_e32 v127, 6, v130
	v_and_b32_e32 v127, 31, v127
	v_lshl_add_u32 v109, v127, 3, v126
	v_lshlrev_b32_e32 v129, 2, v117
	s_cmp_eq_u32 s51, 0
	s_cbranch_scc0 .Lm_mbwd_2
	v_add_u32_e32 v130, 0, v129
	v_cmp_le_u32_e64 s[64:65], v116, v130
	v_add_u32_e32 v130, 1, v129
	v_cmp_le_u32_e64 s[66:67], v116, v130
	v_add_u32_e32 v130, 2, v129
	v_cmp_le_u32_e64 s[68:69], v116, v130
	v_add_u32_e32 v130, 3, v129
	v_cmp_le_u32_e64 s[70:71], v116, v130
	v_add_u32_e32 v130, 8, v129
	v_cmp_le_u32_e64 s[72:73], v116, v130
	v_add_u32_e32 v130, 9, v129
	v_cmp_le_u32_e64 s[74:75], v116, v130
	v_add_u32_e32 v130, 10, v129
	v_cmp_le_u32_e64 s[76:77], v116, v130
	v_add_u32_e32 v130, 11, v129
	v_cmp_le_u32_e64 s[78:79], v116, v130
	v_add_u32_e32 v130, 16, v129
	v_cmp_le_u32_e64 s[80:81], v116, v130
	v_add_u32_e32 v130, 17, v129
	v_cmp_le_u32_e64 s[82:83], v116, v130
	v_add_u32_e32 v130, 18, v129
	v_cmp_le_u32_e64 s[84:85], v116, v130
	v_add_u32_e32 v130, 19, v129
	v_cmp_le_u32_e64 s[86:87], v116, v130
	v_add_u32_e32 v130, 24, v129
	v_cmp_le_u32_e64 s[88:89], v116, v130
	v_add_u32_e32 v130, 25, v129
	v_cmp_le_u32_e64 s[90:91], v116, v130
	v_add_u32_e32 v130, 26, v129
	v_cmp_le_u32_e64 s[92:93], v116, v130
	v_add_u32_e32 v130, 27, v129
	v_cmp_le_u32_e64 s[94:95], v116, v130
	s_branch .Lm_mdone_3

.Lm_t0join_15:
	s_add_u32 s38, s38, s46
	s_addc_u32 s39, s39, s55
	s_add_u32 s40, s40, s47
	s_addc_u32 s41, s41, s55
	ds_write_b64 v224, v[148:149] offset:0
	ds_write_b64 v3, v[150:151] offset:0
	ds_write_b64 v108, v[152:153] offset:0
	ds_write_b64 v109, v[154:155] offset:0
	ds_read_b128 v[176:179], v173 offset:0
	ds_read_b128 v[180:183], v173 offset:32
	ds_read_b128 v[184:187], v173 offset:64
	ds_read_b128 v[188:191], v173 offset:96
	ds_read_b128 v[192:195], v173 offset:128
	ds_read_b128 v[196:199], v173 offset:160
	ds_read_b128 v[200:203], v173 offset:192
	ds_read_b128 v[204:207], v173 offset:224
	ds_read_b32 v2, v211 offset:0
	s_cmp_eq_u32 s54, 0
	s_cbranch_scc0 .Lm_t1diag_16
	v_sub_f32_e32 v132, v234, v251
	v_sub_f32_e32 v133, v235, v251
	v_sub_f32_e32 v134, v236, v251
	v_sub_f32_e32 v135, v237, v251
	v_sub_f32_e32 v136, v238, v251
	v_sub_f32_e32 v137, v239, v251
	v_sub_f32_e32 v138, v240, v251
	v_sub_f32_e32 v139, v241, v251
	v_sub_f32_e32 v140, v242, v251
	v_sub_f32_e32 v141, v243, v251
	v_sub_f32_e32 v142, v244, v251
	v_sub_f32_e32 v143, v245, v251
	v_sub_f32_e32 v144, v246, v251
	v_sub_f32_e32 v145, v247, v251
	v_sub_f32_e32 v146, v248, v251
	v_sub_f32_e32 v147, v249, v251
	v_exp_f32_e32 v132, v132
	v_exp_f32_e32 v133, v133
	v_exp_f32_e32 v134, v134
	v_exp_f32_e32 v135, v135
	v_exp_f32_e32 v136, v136
	v_exp_f32_e32 v137, v137
	v_exp_f32_e32 v138, v138
	v_exp_f32_e32 v139, v139
	v_exp_f32_e32 v140, v140
	v_exp_f32_e32 v141, v141
	v_exp_f32_e32 v142, v142
	v_exp_f32_e32 v143, v143
	v_exp_f32_e32 v144, v144
	v_exp_f32_e32 v145, v145
	v_exp_f32_e32 v146, v146
	v_exp_f32_e32 v147, v147
	v_mul_f32_e32 v92, v92, v132
	v_mul_f32_e32 v93, v93, v133
	v_mul_f32_e32 v94, v94, v134
	v_mul_f32_e32 v95, v95, v135
	v_mul_f32_e32 v96, v96, v136
	v_mul_f32_e32 v97, v97, v137
	v_mul_f32_e32 v98, v98, v138
	v_mul_f32_e32 v99, v99, v139
	v_mul_f32_e32 v100, v100, v140
	v_mul_f32_e32 v101, v101, v141
	v_mul_f32_e32 v102, v102, v142
	v_mul_f32_e32 v103, v103, v143
	v_mul_f32_e32 v104, v104, v144
	v_mul_f32_e32 v105, v105, v145
	v_mul_f32_e32 v106, v106, v146
	v_mul_f32_e32 v107, v107, v147
	v_cvt_pk_bf16_f32 v148, v92, v93
	v_cvt_pk_bf16_f32 v149, v94, v95
	v_cvt_pk_bf16_f32 v150, v96, v97
	v_cvt_pk_bf16_f32 v151, v98, v99
	v_cvt_pk_bf16_f32 v152, v100, v101
	v_cvt_pk_bf16_f32 v153, v102, v103
	v_cvt_pk_bf16_f32 v154, v104, v105
	v_cvt_pk_bf16_f32 v155, v106, v107
	s_branch .Lm_t1join_17

.Lm_t1join_17:
	ds_write_b64 v224, v[148:149] offset:8192
	ds_write_b64 v3, v[150:151] offset:8192
	ds_write_b64 v108, v[152:153] offset:8192
	ds_write_b64 v109, v[154:155] offset:8192
	s_branch .Lm_adone_11

.Lm_nodiag_18:
	v_cvt_pk_bf16_f32 v132, v76, v77
	v_cvt_pk_bf16_f32 v133, v78, v79
	v_cvt_pk_bf16_f32 v134, v80, v81
	v_cvt_pk_bf16_f32 v135, v82, v83
	v_cvt_pk_bf16_f32 v136, v84, v85
	v_cvt_pk_bf16_f32 v137, v86, v87
	v_cvt_pk_bf16_f32 v138, v88, v89
	v_cvt_pk_bf16_f32 v139, v90, v91
	ds_write_b64 v224, v[132:133] offset:0
	ds_write_b64 v3, v[134:135] offset:0
	ds_write_b64 v108, v[136:137] offset:0
	ds_write_b64 v109, v[138:139] offset:0
	s_branch .Lm_adone_11

.Lm_sjoin_20:
	ds_write_b64 v224, v[156:157] offset:0
	ds_write_b64 v3, v[158:159] offset:0
	ds_write_b64 v108, v[160:161] offset:0
	ds_write_b64 v109, v[162:163] offset:0
	s_nop 7
	v_cvt_pk_bf16_f32 v140, v176, v177
	v_cvt_pk_bf16_f32 v141, v178, v179
	v_cvt_pk_bf16_f32 v142, v180, v181
	v_cvt_pk_bf16_f32 v143, v182, v183
	v_cvt_pk_bf16_f32 v144, v184, v185
	v_cvt_pk_bf16_f32 v145, v186, v187
	v_cvt_pk_bf16_f32 v146, v188, v189
	v_cvt_pk_bf16_f32 v147, v190, v191
	ds_write_b64 v194, v[140:141] offset:8704
	ds_write_b64 v194, v[142:143] offset:8720
	ds_write_b64 v194, v[144:145] offset:8736
	ds_write_b64 v194, v[146:147] offset:8752
	s_branch .Lm_adone_11

.Lm_noscan_21:
.Lm_adone_11:
	s_waitcnt lgkmcnt(0)
	s_barrier
	s_cmp_lt_u32 s3, 4
	s_cbranch_scc0 .Lm_noy_23
	ds_read_b64_tr_b16 v[116:117], v208 offset:0
	ds_read_b64_tr_b16 v[118:119], v208 offset:256
	ds_read_b64_tr_b16 v[120:121], v209 offset:0
	ds_read_b64_tr_b16 v[122:123], v110 offset:0
	ds_read_b128 v[124:127], v210 offset:0
	ds_read_b64_tr_b16 v[128:129], v208 offset:1024
	ds_read_b64_tr_b16 v[130:131], v208 offset:1280
	ds_read_b64_tr_b16 v[132:133], v209 offset:4096
	ds_read_b64_tr_b16 v[134:135], v110 offset:4096
	ds_read_b128 v[136:139], v210 offset:32
	ds_read_b64_tr_b16 v[140:141], v208 offset:2048
	ds_read_b64_tr_b16 v[142:143], v208 offset:2304
	ds_read_b64_tr_b16 v[144:145], v209 offset:8192
	ds_read_b64_tr_b16 v[146:147], v110 offset:8192
	ds_read_b128 v[148:151], v210 offset:64
	s_waitcnt lgkmcnt(10)
	v_mfma_f32_32x32x16_bf16 v[76:91], v[116:119], v[120:123], 0
	v_mfma_f32_32x32x16_bf16 v[92:107], v[124:127], v[176:179], 0
	ds_read_b64_tr_b16 v[116:117], v208 offset:3072
	ds_read_b64_tr_b16 v[118:119], v208 offset:3328
	ds_read_b64_tr_b16 v[120:121], v209 offset:12288
	ds_read_b64_tr_b16 v[122:123], v110 offset:12288
	ds_read_b128 v[124:127], v210 offset:96
	s_waitcnt lgkmcnt(10)
	v_mfma_f32_32x32x16_bf16 v[76:91], v[128:131], v[132:135], v[76:91]
	v_mfma_f32_32x32x16_bf16 v[92:107], v[136:139], v[180:183], v[92:107]
	ds_read_b64_tr_b16 v[128:129], v208 offset:4096
	ds_read_b64_tr_b16 v[130:131], v208 offset:4352
	ds_read_b64_tr_b16 v[132:133], v209 offset:16384
	ds_read_b64_tr_b16 v[134:135], v110 offset:16384
	ds_read_b128 v[136:139], v210 offset:128
	s_waitcnt lgkmcnt(10)
	v_mfma_f32_32x32x16_bf16 v[76:91], v[140:143], v[144:147], v[76:91]
	v_mfma_f32_32x32x16_bf16 v[92:107], v[148:151], v[184:187], v[92:107]
	ds_read_b64_tr_b16 v[140:141], v208 offset:5120
	ds_read_b64_tr_b16 v[142:143], v208 offset:5376
	ds_read_b64_tr_b16 v[144:145], v209 offset:20480
	ds_read_b64_tr_b16 v[146:147], v110 offset:20480
	ds_read_b128 v[148:151], v210 offset:160
	s_waitcnt lgkmcnt(10)
	v_mfma_f32_32x32x16_bf16 v[76:91], v[116:119], v[120:123], v[76:91]
	v_mfma_f32_32x32x16_bf16 v[92:107], v[124:127], v[188:191], v[92:107]
	ds_read_b64_tr_b16 v[116:117], v208 offset:6144
	ds_read_b64_tr_b16 v[118:119], v208 offset:6400
	ds_read_b64_tr_b16 v[120:121], v209 offset:24576
	ds_read_b64_tr_b16 v[122:123], v110 offset:24576
	ds_read_b128 v[124:127], v210 offset:192
	s_waitcnt lgkmcnt(10)
	v_mfma_f32_32x32x16_bf16 v[76:91], v[128:131], v[132:135], v[76:91]
	v_mfma_f32_32x32x16_bf16 v[92:107], v[136:139], v[192:195], v[92:107]
	ds_read_b64_tr_b16 v[128:129], v208 offset:7168
	ds_read_b64_tr_b16 v[130:131], v208 offset:7424
	ds_read_b64_tr_b16 v[132:133], v209 offset:28672
	ds_read_b64_tr_b16 v[134:135], v110 offset:28672
	ds_read_b128 v[136:139], v210 offset:224
	s_waitcnt lgkmcnt(10)
	v_mfma_f32_32x32x16_bf16 v[76:91], v[140:143], v[144:147], v[76:91]
	v_mfma_f32_32x32x16_bf16 v[92:107], v[148:151], v[196:199], v[92:107]
	s_waitcnt lgkmcnt(5)
	v_mfma_f32_32x32x16_bf16 v[76:91], v[116:119], v[120:123], v[76:91]
	v_mfma_f32_32x32x16_bf16 v[92:107], v[124:127], v[200:203], v[92:107]
	s_waitcnt lgkmcnt(0)
	v_mfma_f32_32x32x16_bf16 v[76:91], v[128:131], v[132:135], v[76:91]
	v_mfma_f32_32x32x16_bf16 v[92:107], v[136:139], v[204:207], v[92:107]

.Lm_t0join_39:
	s_add_u32 s38, s38, s46
	s_addc_u32 s39, s39, s55
	s_add_u32 s40, s40, s47
	s_addc_u32 s41, s41, s55
	ds_write_b64 v224, v[148:149] offset:0
	ds_write_b64 v3, v[150:151] offset:0
	ds_write_b64 v108, v[152:153] offset:0
	ds_write_b64 v109, v[154:155] offset:0
	ds_read_b128 v[176:179], v173 offset:0
	ds_read_b128 v[180:183], v173 offset:32
	ds_read_b128 v[184:187], v173 offset:64
	ds_read_b128 v[188:191], v173 offset:96
	ds_read_b128 v[192:195], v173 offset:128
	ds_read_b128 v[196:199], v173 offset:160
	ds_read_b128 v[200:203], v173 offset:192
	ds_read_b128 v[204:207], v173 offset:224
	ds_read_b32 v2, v211 offset:2048
	s_cmp_eq_u32 s54, 0
	s_cbranch_scc0 .Lm_t1diag_40
	v_sub_f32_e32 v132, v234, v251
	v_sub_f32_e32 v133, v235, v251
	v_sub_f32_e32 v134, v236, v251
	v_sub_f32_e32 v135, v237, v251
	v_sub_f32_e32 v136, v238, v251
	v_sub_f32_e32 v137, v239, v251
	v_sub_f32_e32 v138, v240, v251
	v_sub_f32_e32 v139, v241, v251
	v_sub_f32_e32 v140, v242, v251
	v_sub_f32_e32 v141, v243, v251
	v_sub_f32_e32 v142, v244, v251
	v_sub_f32_e32 v143, v245, v251
	v_sub_f32_e32 v144, v246, v251
	v_sub_f32_e32 v145, v247, v251
	v_sub_f32_e32 v146, v248, v251
	v_sub_f32_e32 v147, v249, v251
	v_exp_f32_e32 v132, v132
	v_exp_f32_e32 v133, v133
	v_exp_f32_e32 v134, v134
	v_exp_f32_e32 v135, v135
	v_exp_f32_e32 v136, v136
	v_exp_f32_e32 v137, v137
	v_exp_f32_e32 v138, v138
	v_exp_f32_e32 v139, v139
	v_exp_f32_e32 v140, v140
	v_exp_f32_e32 v141, v141
	v_exp_f32_e32 v142, v142
	v_exp_f32_e32 v143, v143
	v_exp_f32_e32 v144, v144
	v_exp_f32_e32 v145, v145
	v_exp_f32_e32 v146, v146
	v_exp_f32_e32 v147, v147
	v_mul_f32_e32 v92, v92, v132
	v_mul_f32_e32 v93, v93, v133
	v_mul_f32_e32 v94, v94, v134
	v_mul_f32_e32 v95, v95, v135
	v_mul_f32_e32 v96, v96, v136
	v_mul_f32_e32 v97, v97, v137
	v_mul_f32_e32 v98, v98, v138
	v_mul_f32_e32 v99, v99, v139
	v_mul_f32_e32 v100, v100, v140
	v_mul_f32_e32 v101, v101, v141
	v_mul_f32_e32 v102, v102, v142
	v_mul_f32_e32 v103, v103, v143
	v_mul_f32_e32 v104, v104, v144
	v_mul_f32_e32 v105, v105, v145
	v_mul_f32_e32 v106, v106, v146
	v_mul_f32_e32 v107, v107, v147
	v_cvt_pk_bf16_f32 v148, v92, v93
	v_cvt_pk_bf16_f32 v149, v94, v95
	v_cvt_pk_bf16_f32 v150, v96, v97
	v_cvt_pk_bf16_f32 v151, v98, v99
	v_cvt_pk_bf16_f32 v152, v100, v101
	v_cvt_pk_bf16_f32 v153, v102, v103
	v_cvt_pk_bf16_f32 v154, v104, v105
	v_cvt_pk_bf16_f32 v155, v106, v107
	s_branch .Lm_t1join_41

.Lm_sjoin_44:
	ds_write_b64 v224, v[156:157] offset:0
	ds_write_b64 v3, v[158:159] offset:0
	ds_write_b64 v108, v[160:161] offset:0
	ds_write_b64 v109, v[162:163] offset:0
	s_nop 7
	v_cvt_pk_bf16_f32 v140, v176, v177
	v_cvt_pk_bf16_f32 v141, v178, v179
	v_cvt_pk_bf16_f32 v142, v180, v181
	v_cvt_pk_bf16_f32 v143, v182, v183
	v_cvt_pk_bf16_f32 v144, v184, v185
	v_cvt_pk_bf16_f32 v145, v186, v187
	v_cvt_pk_bf16_f32 v146, v188, v189
	v_cvt_pk_bf16_f32 v147, v190, v191
	ds_write_b64 v194, v[140:141] offset:0
	ds_write_b64 v194, v[142:143] offset:16
	ds_write_b64 v194, v[144:145] offset:32
	ds_write_b64 v194, v[146:147] offset:48
	s_branch .Lm_adone_35

.Lm_noscan_45:
.Lm_adone_35:
	s_waitcnt lgkmcnt(0)
	s_barrier
	s_cmp_lt_u32 s3, 4
	s_cbranch_scc0 .Lm_noy_47
	ds_read_b64_tr_b16 v[116:117], v208 offset:43008
	ds_read_b64_tr_b16 v[118:119], v208 offset:43264
	ds_read_b64_tr_b16 v[120:121], v209 offset:0
	ds_read_b64_tr_b16 v[122:123], v110 offset:0
	ds_read_b128 v[124:127], v210 offset:8704
	ds_read_b64_tr_b16 v[128:129], v208 offset:44032
	ds_read_b64_tr_b16 v[130:131], v208 offset:44288
	ds_read_b64_tr_b16 v[132:133], v209 offset:4096
	ds_read_b64_tr_b16 v[134:135], v110 offset:4096
	ds_read_b128 v[136:139], v210 offset:8736
	ds_read_b64_tr_b16 v[140:141], v208 offset:45056
	ds_read_b64_tr_b16 v[142:143], v208 offset:45312
	ds_read_b64_tr_b16 v[144:145], v209 offset:8192
	ds_read_b64_tr_b16 v[146:147], v110 offset:8192
	ds_read_b128 v[148:151], v210 offset:8768
	s_waitcnt lgkmcnt(10)
	v_mfma_f32_32x32x16_bf16 v[76:91], v[116:119], v[120:123], 0
	v_mfma_f32_32x32x16_bf16 v[92:107], v[124:127], v[176:179], 0
	ds_read_b64_tr_b16 v[116:117], v208 offset:46080
	ds_read_b64_tr_b16 v[118:119], v208 offset:46336
	ds_read_b64_tr_b16 v[120:121], v209 offset:12288
	ds_read_b64_tr_b16 v[122:123], v110 offset:12288
	ds_read_b128 v[124:127], v210 offset:8800
	s_waitcnt lgkmcnt(10)
	v_mfma_f32_32x32x16_bf16 v[76:91], v[128:131], v[132:135], v[76:91]
	v_mfma_f32_32x32x16_bf16 v[92:107], v[136:139], v[180:183], v[92:107]
	ds_read_b64_tr_b16 v[128:129], v208 offset:47104
	ds_read_b64_tr_b16 v[130:131], v208 offset:47360
	ds_read_b64_tr_b16 v[132:133], v209 offset:16384
	ds_read_b64_tr_b16 v[134:135], v110 offset:16384
	ds_read_b128 v[136:139], v210 offset:8832
	s_waitcnt lgkmcnt(10)
	v_mfma_f32_32x32x16_bf16 v[76:91], v[140:143], v[144:147], v[76:91]
	v_mfma_f32_32x32x16_bf16 v[92:107], v[148:151], v[184:187], v[92:107]
	ds_read_b64_tr_b16 v[140:141], v208 offset:48128
	ds_read_b64_tr_b16 v[142:143], v208 offset:48384
	ds_read_b64_tr_b16 v[144:145], v209 offset:20480
	ds_read_b64_tr_b16 v[146:147], v110 offset:20480
	ds_read_b128 v[148:151], v210 offset:8864
	s_waitcnt lgkmcnt(10)
	v_mfma_f32_32x32x16_bf16 v[76:91], v[116:119], v[120:123], v[76:91]
	v_mfma_f32_32x32x16_bf16 v[92:107], v[124:127], v[188:191], v[92:107]
	ds_read_b64_tr_b16 v[116:117], v208 offset:49152
	ds_read_b64_tr_b16 v[118:119], v208 offset:49408
	ds_read_b64_tr_b16 v[120:121], v209 offset:24576
	ds_read_b64_tr_b16 v[122:123], v110 offset:24576
	ds_read_b128 v[124:127], v210 offset:8896
	s_waitcnt lgkmcnt(10)
	v_mfma_f32_32x32x16_bf16 v[76:91], v[128:131], v[132:135], v[76:91]
	v_mfma_f32_32x32x16_bf16 v[92:107], v[136:139], v[192:195], v[92:107]
	ds_read_b64_tr_b16 v[128:129], v208 offset:50176
	ds_read_b64_tr_b16 v[130:131], v208 offset:50432
	ds_read_b64_tr_b16 v[132:133], v209 offset:28672
	ds_read_b64_tr_b16 v[134:135], v110 offset:28672
	ds_read_b128 v[136:139], v210 offset:8928
	s_waitcnt lgkmcnt(10)
	v_mfma_f32_32x32x16_bf16 v[76:91], v[140:143], v[144:147], v[76:91]
	v_mfma_f32_32x32x16_bf16 v[92:107], v[148:151], v[196:199], v[92:107]
	s_waitcnt lgkmcnt(5)
	v_mfma_f32_32x32x16_bf16 v[76:91], v[116:119], v[120:123], v[76:91]
	v_mfma_f32_32x32x16_bf16 v[92:107], v[124:127], v[200:203], v[92:107]
	s_waitcnt lgkmcnt(0)
	v_mfma_f32_32x32x16_bf16 v[76:91], v[128:131], v[132:135], v[76:91]
	v_mfma_f32_32x32x16_bf16 v[92:107], v[136:139], v[204:207], v[92:107]
